# E2b: the k=S/2 row jobs are done only by the CUs that run the short DFT unit (6 jobs per wave); long-unit CUs skip the prelude
# speedup vs baseline: 1.0048x; 1.0048x over previous
; __device__ __forceinline__ unsigned cvt_pk_bf16(float lo, float hi) { unsigned r; asm("v_cvt_pk_bf16_f32 %0, %1, %2" : "=v"(r) : "v"(lo), "v"(hi)); return r; }
; template <int layer>
; __device__ __forceinline__ void run_layer(LAS unsigned char* lds, const XcdBarrier& xb) {
;     ...
;                 for (int job = gw; job < 12 * 512; job += NGW) {
;                     const int seq = job >> 9, ch = job & 511;
;                     const int S = seq < 8 ? 2048 : 4096; const size_t tok0 = seq < 8 ? (size_t)seq * 2048 : (size_t)TP + (size_t)(seq - 8) * 4096;
;                     const bf16_t* fp = FT + (size_t)ch * T + tok0;
;                     float a = 0.f;
;                     for (int s0 = lane * 8; s0 < S; s0 += 512) { const u32x4 v = *(const u32x4*)(fp + s0);
; #pragma unroll
;                         for (int e = 0; e < 4; ++e) a += bf_lo(v[e]) - bf_hi(v[e]); }
;                     a = wave_sum(a) * (S == 2048 ? 0.02209708691207961f : 0.015625f);
;                     if (lane == 0) { bf16_t* o = PQ + (tok0 + S / 2) * 1024 + (ch >> 7) * 256 + (ch & 127); o[0] = (bf16_t)(cvt_pk_bf16(a, 0.f) & 0xffffu); o[128] = 0; }
.LBB0_405:
	s_or_b64 exec, exec, s[4:5]
	s_mov_b64 s[0:1], s[92:93]
	s_barrier
	s_load_dwordx2 s[10:11], s[0:1], 0x88
	v_mov_b32_e32 v0, v254
	v_readlane_b32 s0, v255, 0
	v_ashrrev_i32_e32 v1, 6, v0
	s_nop 0
	v_add_u32_e32 v8, s0, v1
	v_add_u32_e32 v8, 0xfffffc00, v8
	s_movk_i32 s0, 0x1800
	v_cmp_gt_u32_e32 vcc, s0, v8
	s_and_saveexec_b64 s[8:9], vcc
	s_cbranch_execz .LBB0_416
	v_mbcnt_lo_u32_b32 v1, -1, 0
	v_mbcnt_hi_u32_b32 v1, -1, v1
	v_and_b32_e32 v2, 64, v1
	v_add_u32_e32 v2, 64, v2
	v_xor_b32_e32 v3, 1, v1
	v_cmp_lt_i32_e32 vcc, v3, v2
	v_lshrrev_b32_e32 v4, 6, v0
	v_and_b32_e32 v0, 63, v0
	v_cndmask_b32_e32 v3, v1, v3, vcc
	v_lshlrev_b32_e32 v10, 2, v3
	v_xor_b32_e32 v3, 2, v1
	v_cmp_lt_i32_e32 vcc, v3, v2
	v_lshlrev_b32_e32 v9, 3, v0
	s_mov_b64 s[0:1], 0x1ce00000
	v_cndmask_b32_e32 v3, v1, v3, vcc
	v_lshlrev_b32_e32 v11, 2, v3
	v_xor_b32_e32 v3, 4, v1
	v_cmp_lt_i32_e32 vcc, v3, v2
	s_mov_b64 s[20:21], 0
	s_mov_b64 s[22:23], 0x4000
	v_cndmask_b32_e32 v3, v1, v3, vcc
	v_lshlrev_b32_e32 v12, 2, v3
	v_xor_b32_e32 v3, 8, v1
	v_cmp_lt_i32_e32 vcc, v3, v2
	v_mov_b32_e32 v17, 0x1000
	v_mov_b32_e32 v18, 0x800
	v_cndmask_b32_e32 v3, v1, v3, vcc
	v_lshlrev_b32_e32 v13, 2, v3
	v_xor_b32_e32 v3, 16, v1
	v_cmp_lt_i32_e32 vcc, v3, v2
	s_mov_b64 s[24:25], 0x400
	v_mov_b32_e32 v19, 0x3c800000
	v_cndmask_b32_e32 v3, v1, v3, vcc
	v_lshlrev_b32_e32 v14, 2, v3
	v_xor_b32_e32 v3, 32, v1
	v_cmp_lt_i32_e32 vcc, v3, v2
	v_mov_b32_e32 v20, 0x3cb504f3
	s_nop 0
	v_cndmask_b32_e32 v1, v1, v3, vcc
	v_lshlrev_b32_e32 v15, 2, v1
	v_cmp_eq_u32_e32 vcc, 0, v0
	v_lshlrev_b32_e32 v0, 4, v0
	v_mov_b32_e32 v1, 0
	v_lshl_add_u64 v[2:3], s[36:37], 0, v[0:1]
	v_lshl_add_u64 v[2:3], v[2:3], 0, s[0:1]
	v_readlane_b32 s0, v255, 0
	s_movk_i32 s1, 0x17ff
	s_nop 0
	v_add_u16_e32 v16, s0, v4
	s_movk_i32 s0, 0x1ff
	s_branch .LBB0_408
.LBB0_407:
	s_or_b64 exec, exec, s[6:7]
	v_add_u32_e32 v8, 0x400, v8
	v_cmp_lt_i32_e64 s[4:5], s1, v8
	s_or_b64 s[20:21], s[4:5], s[20:21]
	v_add_u16_e32 v16, s40, v16
	s_andn2_b64 exec, exec, s[20:21]
	s_cbranch_execz .LBB0_416

; __device__ __forceinline__ unsigned cvt_pk_bf16(float lo, float hi) { unsigned r; asm("v_cvt_pk_bf16_f32 %0, %1, %2" : "=v"(r) : "v"(lo), "v"(hi)); return r; }
; template <int layer>
; __device__ __forceinline__ void run_layer(LAS unsigned char* lds, const XcdBarrier& xb) {
;     ...
;                 for (int job = gw; job < 12 * 512; job += NGW) {
;                     const int seq = job >> 9, ch = job & 511;
;                     const int S = seq < 8 ? 2048 : 4096; const size_t tok0 = seq < 8 ? (size_t)seq * 2048 : (size_t)TP + (size_t)(seq - 8) * 4096;
;                     const bf16_t* fp = FT + (size_t)ch * T + tok0;
;                     float a = 0.f;
;                     for (int s0 = lane * 8; s0 < S; s0 += 512) { const u32x4 v = *(const u32x4*)(fp + s0);
; #pragma unroll
;                         for (int e = 0; e < 4; ++e) a += bf_lo(v[e]) - bf_hi(v[e]); }
;                     a = wave_sum(a) * (S == 2048 ? 0.02209708691207961f : 0.015625f);
;                     if (lane == 0) { bf16_t* o = PQ + (tok0 + S / 2) * 1024 + (ch >> 7) * 256 + (ch & 127); o[0] = (bf16_t)(cvt_pk_bf16(a, 0.f) & 0xffffu); o[128] = 0; }
.LBB0_1158:
	s_or_b64 exec, exec, s[8:9]
	s_mov_b64 s[0:1], s[82:83]
	s_barrier
	s_load_dwordx2 s[16:17], s[0:1], 0x88
	v_mov_b32_e32 v0, v254
	v_readlane_b32 s0, v255, 0
	v_ashrrev_i32_e32 v1, 6, v0
	s_nop 0
	v_add_u32_e32 v8, s0, v1
	v_add_u32_e32 v8, 0xfffffc00, v8
	s_movk_i32 s0, 0x1800
	v_cmp_gt_u32_e32 vcc, s0, v8
	s_and_saveexec_b64 s[12:13], vcc
	s_cbranch_execz .LBB0_1169
	v_mbcnt_lo_u32_b32 v1, -1, 0
	v_mbcnt_hi_u32_b32 v1, -1, v1
	v_and_b32_e32 v2, 64, v1
	v_add_u32_e32 v2, 64, v2
	v_xor_b32_e32 v3, 1, v1
	v_cmp_lt_i32_e32 vcc, v3, v2
	v_lshrrev_b32_e32 v4, 6, v0
	v_and_b32_e32 v0, 63, v0
	v_cndmask_b32_e32 v3, v1, v3, vcc
	v_lshlrev_b32_e32 v10, 2, v3
	v_xor_b32_e32 v3, 2, v1
	v_cmp_lt_i32_e32 vcc, v3, v2
	v_lshlrev_b32_e32 v9, 3, v0
	s_mov_b64 s[0:1], 0x1ce00000
	v_cndmask_b32_e32 v3, v1, v3, vcc
	v_lshlrev_b32_e32 v11, 2, v3
	v_xor_b32_e32 v3, 4, v1
	v_cmp_lt_i32_e32 vcc, v3, v2
	s_mov_b64 s[18:19], 0
	v_mov_b32_e32 v17, 0x1000
	v_cndmask_b32_e32 v3, v1, v3, vcc
	v_lshlrev_b32_e32 v12, 2, v3
	v_xor_b32_e32 v3, 8, v1
	v_cmp_lt_i32_e32 vcc, v3, v2
	v_mov_b32_e32 v18, 0x800
	s_mov_b64 s[50:51], 0x400
	v_cndmask_b32_e32 v3, v1, v3, vcc
	v_lshlrev_b32_e32 v13, 2, v3
	v_xor_b32_e32 v3, 16, v1
	v_cmp_lt_i32_e32 vcc, v3, v2
	v_mov_b32_e32 v19, 0x3c800000
	v_mov_b32_e32 v20, 0x3cb504f3
	v_cndmask_b32_e32 v3, v1, v3, vcc
	v_lshlrev_b32_e32 v14, 2, v3
	v_xor_b32_e32 v3, 32, v1
	v_cmp_lt_i32_e32 vcc, v3, v2
	s_nop 1
	v_cndmask_b32_e32 v1, v1, v3, vcc
	v_lshlrev_b32_e32 v15, 2, v1
	v_cmp_eq_u32_e32 vcc, 0, v0
	v_lshlrev_b32_e32 v0, 4, v0
	v_mov_b32_e32 v1, 0
	v_lshl_add_u64 v[2:3], s[48:49], 0, v[0:1]
	v_lshl_add_u64 v[2:3], v[2:3], 0, s[0:1]
	v_readlane_b32 s0, v255, 0
	s_mov_b64 s[48:49], 0x4000
	s_movk_i32 s1, 0x17ff
	v_add_u16_e32 v16, s0, v4
	s_movk_i32 s0, 0x1ff
	s_branch .LBB0_1161
.LBB0_1160:
	s_or_b64 exec, exec, s[10:11]
	v_add_u32_e32 v8, 0x400, v8
	v_cmp_lt_i32_e64 s[8:9], s1, v8
	s_or_b64 s[18:19], s[8:9], s[18:19]
	v_add_u16_e32 v16, s40, v16
	s_andn2_b64 exec, exec, s[18:19]
	s_cbranch_execz .LBB0_1169
